# P3SP: software-pipelined P3 loop (next item pair's loads issued before the current pair's arithmetic) on top of G2b
# speedup vs baseline: 1.0055x; 1.0055x over previous
; #define INP(k) inp_ptr(a, k)
; #define WSP(type, off) ((type*)(ws_opaque(a) + (off)))
; __global__ void __launch_bounds__(NTHR, 2) mega_fwd(Args a) {
;     ...
;             float* OATT = WSP(float, WS_R1); bf16_t* Y = WSP(bf16_t, WS_Y); float* lamp = WSP(float, WS_LAM);
;             const float lam_init = 0.8f - 0.6f * expf(-0.3f * (float)l);
;             const float lam = lamp[l]; const float* sg = INP(11) + (size_t)l * 256;
;             const f32x4 gv = *(const f32x4*)(sg + 4 * lane);
;             for (int it = gw; it < T * 4; it += 2 * NGW) {
;                 const int half = lane >> 5, e = (lane & 31) * 4;
;                 const int itb = it + NGW;
;                 const int ra = it >> 2, ha = it & 3, ba = ra >> 13, ta = ra & (SEQ - 1);
;                 const int rb = itb >> 2, hb = itb & 3, bb = rb >> 13, tb = rb & (SEQ - 1);
;                 const size_t a0 = ((size_t)(((ba * 4 + ha) * 2 + 0) * 2 + half) * SEQ + ta) * 128 + e, a1 = ((size_t)(((ba * 4 + ha) * 2 + 1) * 2 + half) * SEQ + ta) * 128 + e;
;                 const size_t b0 = ((size_t)(((bb * 4 + hb) * 2 + 0) * 2 + half) * SEQ + tb) * 128 + e, b1 = ((size_t)(((bb * 4 + hb) * 2 + 1) * 2 + half) * SEQ + tb) * 128 + e;
;                 const f32x4 oa0 = *(const f32x4*)(OATT + a0), oa1 = *(const f32x4*)(OATT + a1), ob0 = *(const f32x4*)(OATT + b0), ob1 = *(const f32x4*)(OATT + b1);
.LBB0_688:
	s_or_b64 exec, exec, s[0:1]
	s_mov_b32 s0, s12
	v_mov_b32_e32 v2, v1
	s_waitcnt lgkmcnt(0)
	s_barrier
	s_lshl_b32 s0, s0, 3
	v_readfirstlane_b32 s6, v2
	s_ashr_i32 s1, s6, 6
	s_add_i32 s7, s1, s0
	s_mov_b64 s[2:3], 0
	s_mov_b64 s[0:1], 0
	s_mov_b64 s[4:5], 0
	s_add_u32 s8, s70, s4
	s_addc_u32 s9, s71, s5
	s_lshl_b64 s[4:5], s[76:77], 2
	s_add_u32 s4, s8, s4
	s_addc_u32 s5, s9, s5
	global_load_dword v8, v3, s[4:5]
	s_mov_b64 s[4:5], 0
	s_cmp_gt_i32 s7, 0xffff
	s_cbranch_scc1 .LBB0_691
	s_add_u32 s2, s70, s2
	s_addc_u32 s3, s71, s3
	s_add_u32 s2, s2, 0x20000000
	s_addc_u32 s3, s3, 0
	s_add_u32 s9, s70, s0
	v_readlane_b32 s52, v254, 2
	s_addc_u32 s10, s71, s1
	s_lshl_b64 s[0:1], s[4:5], 2
	v_readlane_b32 s58, v254, 8
	v_readlane_b32 s59, v254, 9
	s_add_u32 s4, s58, s0
	s_addc_u32 s5, s59, s1
	s_lshl_b64 s[0:1], s[76:77], 10
	v_and_b32_e32 v10, 63, v2
	s_add_u32 s0, s4, s0
	s_addc_u32 s1, s5, s1
	v_lshlrev_b32_e32 v4, 4, v10
	global_load_dwordx4 v[4:7], v4, s[0:1]
	v_cvt_f32_u32_e32 v9, s76
	s_mov_b32 s0, 0x3fb8aa3b
	v_bfe_u32 v16, v2, 5, 1
	v_lshlrev_b32_e32 v2, 2, v2
	v_mul_f32_e32 v9, 0xbe99999a, v9
	v_mul_f32_e32 v11, 0x3fb8aa3b, v9
	v_fma_f32 v12, v9, s0, -v11
	v_rndne_f32_e32 v13, v11
	v_fmac_f32_e32 v12, 0x32a5705f, v9
	v_sub_f32_e32 v11, v11, v13
	v_add_f32_e32 v11, v11, v12
	v_exp_f32_e32 v11, v11
	v_cvt_i32_f32_e32 v12, v13
	s_mov_b32 s0, 0xc2ce8ed0
	v_cmp_ngt_f32_e32 vcc, s0, v9
	s_mov_b32 s0, 0x42b17218
	v_ldexp_f32 v11, v11, v12
	v_and_b32_e32 v12, 0x7c, v2
	v_and_b32_e32 v2, 64, v239
	v_cndmask_b32_e32 v11, 0, v11, vcc
	v_cmp_nlt_f32_e32 vcc, s0, v9
	v_mov_b32_e32 v9, 0x7f800000
	v_add_u32_e32 v2, 64, v2
	v_xor_b32_e32 v13, 1, v239
	v_cndmask_b32_e32 v11, v9, v11, vcc
	v_cmp_lt_i32_e32 vcc, v13, v2
	s_bfe_u32 s8, s6, 0x20006
	s_lshl_b32 s0, s8, 9
	v_cndmask_b32_e32 v13, v239, v13, vcc
	v_lshlrev_b32_e32 v17, 2, v13
	v_xor_b32_e32 v13, 2, v239
	v_cmp_lt_i32_e32 vcc, v13, v2
	s_add_u32 s0, s9, s0
	s_addc_u32 s1, s10, 0
	v_cndmask_b32_e32 v13, v239, v13, vcc
	v_lshlrev_b32_e32 v18, 2, v13
	v_xor_b32_e32 v13, 4, v239
	v_cmp_lt_i32_e32 vcc, v13, v2
	v_readlane_b32 s54, v254, 4
	v_readlane_b32 s55, v254, 5
	v_cndmask_b32_e32 v13, v239, v13, vcc
	v_lshlrev_b32_e32 v19, 2, v13
	v_xor_b32_e32 v13, 8, v239
	v_cmp_lt_i32_e32 vcc, v13, v2
	v_readlane_b32 s56, v254, 6
	v_readlane_b32 s57, v254, 7
	v_cndmask_b32_e32 v13, v239, v13, vcc
	v_lshlrev_b32_e32 v20, 2, v13
	v_xor_b32_e32 v13, 16, v239
	v_cmp_lt_i32_e32 vcc, v13, v2
	v_readlane_b32 s66, v254, 16
	v_readlane_b32 s67, v254, 17
	v_cndmask_b32_e32 v13, v239, v13, vcc
	v_lshlrev_b32_e32 v21, 2, v13
	v_xor_b32_e32 v13, 32, v239
	v_cmp_lt_i32_e32 vcc, v13, v2
	s_mov_b32 s55, 0x7ffe0
	v_readlane_b32 s54, v254, 61
	v_cndmask_b32_e32 v2, v239, v13, vcc
	v_lshlrev_b32_e32 v22, 2, v2
	v_mov_b32_e32 v2, 0xbf4ccccd
	v_fmamk_f32 v2, v11, 0x3f19999a, v2
	v_add_f32_e32 v23, 1.0, v2
	v_lshlrev_b32_e32 v2, 3, v10
	v_lshl_add_u64 v[10:11], s[0:1], 0, v[2:3]
	s_mov_b64 s[0:1], 0x28000000
	v_readlane_b32 s67, v254, 60
	s_mov_b32 s66, 0x100000
	s_mov_b64 s[56:57], 0x100000
	s_waitcnt vmcnt(1)
	v_mov_b32_e32 v9, v8
	v_lshl_add_u64 v[10:11], v[10:11], 0, s[0:1]
	v_lshlrev_b32_e32 v2, 2, v12
	v_readlane_b32 s53, v254, 3
	v_readlane_b32 s60, v254, 10
	v_readlane_b32 s61, v254, 11
	v_readlane_b32 s62, v254, 12
	v_readlane_b32 s63, v254, 13
	v_readlane_b32 s64, v254, 14
	v_readlane_b32 s65, v254, 15
	s_mov_b32 s10, s7
	s_ashr_i32 s0, s10, 13
	s_and_b32 s0, s0, 0x3ffffffc
	s_add_i32 s11, s10, s28
	s_or_b32 s0, s0, s8
	v_lshl_or_b32 v56, s0, 2, v16
	s_ashr_i32 s0, s11, 13
	s_and_b32 s0, s0, 0x3ffffffc
	s_or_b32 s0, s0, s8
	v_or_b32_e32 v58, 2, v56
	v_lshl_or_b32 v60, s0, 2, v16
	v_ashrrev_i32_e32 v57, 31, v56
	v_ashrrev_i32_e32 v59, 31, v58
	v_or_b32_e32 v62, 2, v60
	v_ashrrev_i32_e32 v61, 31, v60
	v_ashrrev_i32_e32 v63, 31, v62
	v_lshlrev_b64 v[56:57], 22, v[56:57]
	s_ashr_i32 s0, s10, 2
	s_lshl_b32 s0, s0, 9
	v_lshlrev_b64 v[58:59], 22, v[58:59]
	v_lshl_add_u64 v[56:57], s[2:3], 0, v[56:57]
	s_and_b32 s30, s0, 0x3ffe00
	v_lshl_add_u64 v[58:59], s[2:3], 0, v[58:59]
	v_lshlrev_b64 v[60:61], 22, v[60:61]
	s_ashr_i32 s0, s11, 2
	s_lshl_b32 s0, s0, 9
	v_lshlrev_b64 v[62:63], 22, v[62:63]
	v_lshl_add_u64 v[56:57], v[56:57], 0, s[30:31]
	v_lshl_add_u64 v[58:59], v[58:59], 0, s[30:31]
	v_lshl_add_u64 v[60:61], s[2:3], 0, v[60:61]
	s_and_b32 s30, s0, 0x3ffe00
	v_lshl_add_u64 v[62:63], s[2:3], 0, v[62:63]
	v_lshl_add_u64 v[60:61], v[60:61], 0, s[30:31]
	v_lshl_add_u64 v[62:63], v[62:63], 0, s[30:31]
	v_lshl_add_u64 v[56:57], v[56:57], 0, v[2:3]
	v_lshl_add_u64 v[58:59], v[58:59], 0, v[2:3]
	v_lshl_add_u64 v[60:61], v[60:61], 0, v[2:3]
	v_lshl_add_u64 v[62:63], v[62:63], 0, v[2:3]
	global_load_dwordx4 v[40:43], v[56:57], off
	global_load_dwordx4 v[44:47], v[58:59], off
	global_load_dwordx4 v[48:51], v[60:61], off
	global_load_dwordx4 v[52:55], v[62:63], off
; __device__ __forceinline__ unsigned cvt_pk_bf16(float lo, float hi) { unsigned r; asm volatile("v_cvt_pk_bf16_f32 %0, %1, %2" : "=v"(r) : "v"(lo), "v"(hi)); return r; }
; __global__ void __launch_bounds__(NTHR, 2) mega_fwd(Args a) {
;     ...
;             for (int it = gw; it < T * 4; it += 2 * NGW) {
;                 const int half = lane >> 5, e = (lane & 31) * 4;
;                 const int itb = it + NGW;
;                 const int ra = it >> 2, ha = it & 3, ba = ra >> 13, ta = ra & (SEQ - 1);
;                 const int rb = itb >> 2, hb = itb & 3, bb = rb >> 13, tb = rb & (SEQ - 1);
;                 const size_t a0 = ((size_t)(((ba * 4 + ha) * 2 + 0) * 2 + half) * SEQ + ta) * 128 + e, a1 = ((size_t)(((ba * 4 + ha) * 2 + 1) * 2 + half) * SEQ + ta) * 128 + e;
;                 const size_t b0 = ((size_t)(((bb * 4 + hb) * 2 + 0) * 2 + half) * SEQ + tb) * 128 + e, b1 = ((size_t)(((bb * 4 + hb) * 2 + 1) * 2 + half) * SEQ + tb) * 128 + e;
;                 const f32x4 oa0 = *(const f32x4*)(OATT + a0), oa1 = *(const f32x4*)(OATT + a1), ob0 = *(const f32x4*)(OATT + b0), ob1 = *(const f32x4*)(OATT + b1);
;                 const f32x4 da = oa0 - oa1 * lam, db = ob0 - ob1 * lam;
;                 const float ssa = wave_sum(da[0] * da[0] + da[1] * da[1] + da[2] * da[2] + da[3] * da[3]);
;                 const float ssb = wave_sum(db[0] * db[0] + db[1] * db[1] + db[2] * db[2] + db[3] * db[3]);
;                 const float sca = rsqrtf(ssa * (1.f / 256.f) + LN_EPS) * (1.f - lam_init), scb = rsqrtf(ssb * (1.f / 256.f) + LN_EPS) * (1.f - lam_init);
;                 u32x2 wa; wa.x = cvt_pk_bf16(da[0] * sca * gv[0], da[1] * sca * gv[1]); wa.y = cvt_pk_bf16(da[2] * sca * gv[2], da[3] * sca * gv[3]);
;                 u32x2 wb; wb.x = cvt_pk_bf16(db[0] * scb * gv[0], db[1] * scb * gv[1]); wb.y = cvt_pk_bf16(db[2] * scb * gv[2], db[3] * scb * gv[3]);
;                 *(u32x2*)(Y + (size_t)ra * DM + 1024 + ha * 256 + 4 * lane) = wa;
;                 *(u32x2*)(Y + (size_t)rb * DM + 1024 + hb * 256 + 4 * lane) = wb;
;             }
.LBB0_690:
	s_waitcnt vmcnt(0)
	v_mov_b64_e32 v[12:13], v[40:41]
	v_mov_b64_e32 v[14:15], v[42:43]
	v_mov_b64_e32 v[24:25], v[44:45]
	v_mov_b64_e32 v[26:27], v[46:47]
	v_mov_b64_e32 v[28:29], v[48:49]
	v_mov_b64_e32 v[30:31], v[50:51]
	v_mov_b64_e32 v[32:33], v[52:53]
	v_mov_b64_e32 v[34:35], v[54:55]
	s_add_i32 s9, s7, s28
	s_ashr_i32 s6, s7, 2
	s_ashr_i32 s4, s9, 2
	s_add_i32 s10, s9, s28
	s_cmp_gt_i32 s10, 0xffff
	s_cbranch_scc1 .Lp3_nopf
	s_ashr_i32 s0, s10, 13
	s_and_b32 s0, s0, 0x3ffffffc
	s_add_i32 s11, s10, s28
	s_or_b32 s0, s0, s8
	v_lshl_or_b32 v56, s0, 2, v16
	s_ashr_i32 s0, s11, 13
	s_and_b32 s0, s0, 0x3ffffffc
	s_or_b32 s0, s0, s8
	v_or_b32_e32 v58, 2, v56
	v_lshl_or_b32 v60, s0, 2, v16
	v_ashrrev_i32_e32 v57, 31, v56
	v_ashrrev_i32_e32 v59, 31, v58
	v_or_b32_e32 v62, 2, v60
	v_ashrrev_i32_e32 v61, 31, v60
	v_ashrrev_i32_e32 v63, 31, v62
	v_lshlrev_b64 v[56:57], 22, v[56:57]
	s_ashr_i32 s0, s10, 2
	s_lshl_b32 s0, s0, 9
	v_lshlrev_b64 v[58:59], 22, v[58:59]
	v_lshl_add_u64 v[56:57], s[2:3], 0, v[56:57]
	s_and_b32 s30, s0, 0x3ffe00
	v_lshl_add_u64 v[58:59], s[2:3], 0, v[58:59]
	v_lshlrev_b64 v[60:61], 22, v[60:61]
	s_ashr_i32 s0, s11, 2
	s_lshl_b32 s0, s0, 9
	v_lshlrev_b64 v[62:63], 22, v[62:63]
	v_lshl_add_u64 v[56:57], v[56:57], 0, s[30:31]
	v_lshl_add_u64 v[58:59], v[58:59], 0, s[30:31]
	v_lshl_add_u64 v[60:61], s[2:3], 0, v[60:61]
	s_and_b32 s30, s0, 0x3ffe00
	v_lshl_add_u64 v[62:63], s[2:3], 0, v[62:63]
	v_lshl_add_u64 v[60:61], v[60:61], 0, s[30:31]
	v_lshl_add_u64 v[62:63], v[62:63], 0, s[30:31]
	v_lshl_add_u64 v[56:57], v[56:57], 0, v[2:3]
	v_lshl_add_u64 v[58:59], v[58:59], 0, v[2:3]
	v_lshl_add_u64 v[60:61], v[60:61], 0, v[2:3]
	v_lshl_add_u64 v[62:63], v[62:63], 0, v[2:3]
	global_load_dwordx4 v[40:43], v[56:57], off
	global_load_dwordx4 v[44:47], v[58:59], off
	global_load_dwordx4 v[48:51], v[60:61], off
	global_load_dwordx4 v[52:55], v[62:63], off
.Lp3_nopf:
	v_xor_b32_e32 v36, 0x80000000, v8
	v_mov_b32_e32 v37, v36
	s_mov_b32 s0, 0x3b800000
	s_ashr_i32 s7, s6, 31
	s_ashr_i32 s5, s4, 31
	v_pk_fma_f32 v[14:15], v[36:37], v[26:27], v[14:15]
	v_pk_fma_f32 v[12:13], v[8:9], v[24:25], v[12:13] neg_lo:[1,0,0] neg_hi:[1,0,0]
	v_pk_fma_f32 v[26:27], v[8:9], v[32:33], v[28:29] neg_lo:[1,0,0] neg_hi:[1,0,0]
	v_pk_fma_f32 v[24:25], v[36:37], v[34:35], v[30:31]
	v_pk_mul_f32 v[30:31], v[12:13], v[12:13]
	v_pk_mul_f32 v[34:35], v[26:27], v[26:27]
	v_pk_mul_f32 v[28:29], v[14:15], v[14:15]
	v_pk_mul_f32 v[32:33], v[24:25], v[24:25]
	v_mov_b32_e32 v36, v34
	v_mov_b32_e32 v37, v30
	v_mov_b32_e32 v30, v35
	v_pk_add_f32 v[30:31], v[36:37], v[30:31]
	v_mov_b32_e32 v34, v32
	v_mov_b32_e32 v35, v28
	v_pk_add_f32 v[30:31], v[34:35], v[30:31]
	v_mov_b32_e32 v28, v33
	v_pk_add_f32 v[28:29], v[28:29], v[30:31]
	ds_bpermute_b32 v31, v17, v29
	ds_bpermute_b32 v30, v17, v28
	s_waitcnt lgkmcnt(0)
	v_pk_add_f32 v[28:29], v[28:29], v[30:31]
	ds_bpermute_b32 v31, v18, v29
	ds_bpermute_b32 v30, v18, v28
	s_waitcnt lgkmcnt(0)
	v_pk_add_f32 v[28:29], v[28:29], v[30:31]
	ds_bpermute_b32 v31, v19, v29
	ds_bpermute_b32 v30, v19, v28
	s_waitcnt lgkmcnt(0)
	v_pk_add_f32 v[28:29], v[28:29], v[30:31]
	ds_bpermute_b32 v31, v20, v29
	ds_bpermute_b32 v30, v20, v28
	s_waitcnt lgkmcnt(0)
	v_pk_add_f32 v[28:29], v[28:29], v[30:31]
	ds_bpermute_b32 v31, v21, v29
	ds_bpermute_b32 v30, v21, v28
	s_waitcnt lgkmcnt(0)
	v_pk_add_f32 v[28:29], v[28:29], v[30:31]
	ds_bpermute_b32 v31, v22, v29
	ds_bpermute_b32 v30, v22, v28
	s_waitcnt lgkmcnt(0)
	v_pk_add_f32 v[28:29], v[28:29], v[30:31]
	s_nop 0
	v_pk_fma_f32 v[28:29], v[28:29], s[0:1], v[196:197] op_sel_hi:[1,0,0]
	s_nop 0
	v_mul_f32_e32 v30, 0x4b800000, v29
	v_cmp_gt_f32_e64 s[0:1], s45, v29
	v_cmp_gt_f32_e32 vcc, s45, v28
	s_nop 0
	v_cndmask_b32_e64 v29, v29, v30, s[0:1]
	v_rsq_f32_e32 v29, v29
	s_nop 0
	v_mul_f32_e32 v30, 0x45800000, v29
	v_cndmask_b32_e64 v29, v29, v30, s[0:1]
	v_mul_f32_e32 v30, 0x4b800000, v28
	v_cndmask_b32_e32 v28, v28, v30, vcc
	v_rsq_f32_e32 v28, v28
	v_mul_f32_e32 v29, v23, v29
	v_mul_f32_e32 v12, v12, v29
	v_mul_f32_e32 v13, v13, v29
	v_mul_f32_e32 v30, 0x45800000, v28
	v_mul_f32_e32 v12, v4, v12
	v_mul_f32_e32 v13, v5, v13
	v_cndmask_b32_e32 v28, v28, v30, vcc
	v_cvt_pk_bf16_f32 v12, v12, v13
	v_mul_f32_e32 v13, v14, v29
	v_mul_f32_e32 v14, v15, v29
	v_mul_f32_e32 v28, v23, v28
	v_mul_f32_e32 v13, v6, v13
	v_mul_f32_e32 v14, v7, v14
	v_cvt_pk_bf16_f32 v13, v13, v14
	v_mul_f32_e32 v14, v26, v28
	v_mul_f32_e32 v15, v27, v28
	v_mul_f32_e32 v14, v4, v14
	v_mul_f32_e32 v15, v5, v15
	v_cvt_pk_bf16_f32 v14, v14, v15
	v_mul_f32_e32 v15, v24, v28
	v_mul_f32_e32 v24, v25, v28
	v_mul_f32_e32 v15, v6, v15
	v_mul_f32_e32 v24, v7, v24
	s_lshl_b64 s[0:1], s[6:7], 12
	v_cvt_pk_bf16_f32 v15, v15, v24
	v_lshl_add_u64 v[24:25], v[10:11], 0, s[0:1]
	s_lshl_b64 s[0:1], s[4:5], 12
	s_add_i32 s7, s9, s28
	global_store_dwordx2 v[24:25], v[12:13], off offset:2048
	v_lshl_add_u64 v[12:13], v[10:11], 0, s[0:1]
	s_cmp_gt_i32 s7, 0xffff
	global_store_dwordx2 v[12:13], v[14:15], off offset:2048
	s_cbranch_scc0 .LBB0_690
